# P1: x rows fetched by LDS-DMA as whole 1-KiB contiguous pieces (row image in LDS), read back in the lane layout
# baseline (speedup 1.0000x reference)
; #define GAS __attribute__((address_space(1)))
; template <int LO, int HI> __global__ void __launch_bounds__(NWAVES * 64, 2) fox_fwd(Args args) {
;     ...
;         const int m0 = gw * 16, b = m0 / T;
;         f32x4 gm[4], sh[4];
; #pragma unroll
;         for (int j = 0; j < 4; ++j) { const int col = P1COL(j); const f32x4 g = *(const f32x4*)(norm_g + col), scl = *(const f32x4*)(ADA + b * 3072 + 1024 + col);
;             gm[j] = g * (scl + 1.0f); sh[j] = *(const f32x4*)(ADA + b * 3072 + col); }
;         const float bfv = b_f[lane & 7]; f32x4 lsq[4];
; #pragma unroll
;         for (int k = 0; k < 4; ++k) lsq[k] = (f32x4){0.f, 0.f, 0.f, 0.f};
;         for (int r = 0; r < 16; ++r) { const int m = m0 + r;
;             const GAS float* xr = (const GAS float*)(x + (size_t)m * D);
;             f32x4 v[4]; float s2 = 0.f;
; #pragma unroll
;             for (int j = 0; j < 4; ++j) { v[j] = *(const GAS f32x4*)(xr + P1COL(j)); s2 += (v[j][0] * v[j][0] + v[j][1] * v[j][1]) + (v[j][2] * v[j][2] + v[j][3] * v[j][3]); }
;             const float rstd = 1.0f / sqrtf(wave_sum(s2) * (1.0f / D) + EPS);
.LBB0_130:
	s_or_b64 exec, exec, s[8:9]
	s_ashr_i32 s43, s15, 6
	s_lshl_b32 s8, s14, 3
	s_add_i32 s33, s8, s43
	s_ashr_i32 s8, s33, 31
	s_lshr_b32 s8, s8, 24
	s_add_i32 s8, s33, s8
	s_ashr_i32 s44, s8, 8
	s_mul_i32 s8, s44, 0xc00
	s_ashr_i32 s9, s8, 31
	s_lshl_b64 s[8:9], s[8:9], 2
	s_add_u32 s8, s26, s8
	s_addc_u32 s9, s27, s9
	s_add_u32 s10, s8, 0x1000
	s_addc_u32 s11, s9, 0
	s_lshl_b32 s28, s33, 4
	s_ashr_i32 s29, s28, 31
	s_lshl_b64 s[12:13], s[28:29], 12
	v_and_b32_e32 v1, 63, v34
	s_waitcnt lgkmcnt(0)
	s_add_u32 s30, s6, s12
	v_lshlrev_b32_e32 v54, 5, v1
	s_addc_u32 s31, s7, s13
	s_barrier
	global_load_dwordx4 v[26:29], v54, s[30:31]
	global_load_dwordx4 v[18:21], v54, s[30:31] offset:16
	global_load_dwordx4 v[22:25], v54, s[30:31] offset:2064
	global_load_dwordx4 v[30:33], v54, s[30:31] offset:2048
	global_load_dwordx4 v[38:41], v54, s[10:11] offset:16
	global_load_dwordx4 v[42:45], v54, s[10:11]
	v_mbcnt_lo_u32_b32 v3, -1, 0
	v_and_b32_e32 v2, 7, v34
	v_mbcnt_hi_u32_b32 v35, -1, v3
	v_or_b32_e32 v3, 0x800, v54
	v_lshlrev_b32_e32 v2, 2, v2
	global_load_dwordx4 v[46:49], v3, s[10:11] offset:16
	global_load_dwordx4 v[50:53], v3, s[10:11]
	global_load_dwordx4 v[58:61], v54, s[20:21] offset:16
	global_load_dwordx4 v[62:65], v54, s[20:21]
	global_load_dwordx4 v[74:77], v54, s[20:21] offset:2064
	global_load_dwordx4 v[78:81], v54, s[20:21] offset:2048
	global_load_dword v71, v2, s[4:5]
	v_xor_b32_e32 v83, 16, v35
	v_and_b32_e32 v68, 64, v35
	v_mov_b32_e32 v37, 0
	v_lshlrev_b32_e32 v36, 4, v1
	v_xor_b32_e32 v4, 1, v35
	v_add_u32_e32 v87, 64, v68
	s_mov_b64 s[12:13], 0x2000000
	v_xor_b32_e32 v5, 2, v35
	v_lshl_add_u64 v[2:3], s[26:27], 0, v[36:37]
	v_cmp_lt_i32_e32 vcc, v4, v87
	v_lshl_add_u64 v[56:57], v[2:3], 0, s[12:13]
	v_xor_b32_e32 v55, 4, v35
	v_cndmask_b32_e32 v2, v35, v4, vcc
	v_cmp_lt_i32_e32 vcc, v5, v87
	v_lshlrev_b32_e32 v165, 2, v2
	v_xor_b32_e32 v73, 8, v35
	v_cndmask_b32_e32 v88, v35, v5, vcc
	global_load_dwordx4 v[2:5], v54, s[8:9] offset:16
	global_load_dwordx4 v[6:9], v54, s[8:9]
	v_lshlrev_b32_e32 v169, 2, v88
	v_cmp_lt_i32_e32 vcc, v55, v87
	v_xor_b32_e32 v86, 32, v35
	v_mov_b32_e32 v69, 0x358637bd
	v_cndmask_b32_e32 v55, v35, v55, vcc
	v_lshlrev_b32_e32 v168, 2, v55
	v_cmp_lt_i32_e32 vcc, v73, v87
	s_mov_b32 s45, 0xf800000
	v_mov_b32_e32 v70, 0x260
	v_cndmask_b32_e32 v73, v35, v73, vcc
	v_lshlrev_b32_e32 v167, 2, v73
	v_cmp_lt_i32_e32 vcc, v83, v87
	s_lshl_b64 s[34:35], s[28:29], 11
	v_add_u32_e32 v72, 0, v54
	s_or_b32 s36, s28, 1
	s_ashr_i32 s37, s36, 31
	v_cmp_eq_u32_e64 s[10:11], 4, v1
	v_cmp_eq_u32_e64 s[12:13], 5, v1
	v_cmp_eq_u32_e64 s[14:15], 6, v1
	v_cmp_eq_u32_e64 s[16:17], 7, v1
	s_mov_b32 s29, 0xbfb8aa3b
	s_mov_b32 s46, 0x7f800000
	s_mov_b32 s47, 0x33800000
	s_movk_i32 s48, 0x2000
	s_mov_b64 s[38:39], 0x2800
	s_mov_b64 s[40:41], 0x800
	s_waitcnt vmcnt(14)
	v_pk_mul_f32 v[10:11], v[28:29], v[28:29]
	v_pk_mul_f32 v[12:13], v[26:27], v[26:27]
	s_waitcnt vmcnt(13)
	v_pk_mul_f32 v[14:15], v[20:21], v[20:21]
	v_pk_mul_f32 v[16:17], v[18:19], v[18:19]
	v_pk_mov_b32 v[84:85], v[12:13], v[10:11] op_sel:[1,0]
	v_mov_b32_e32 v13, v11
	v_pk_mov_b32 v[10:11], v[16:17], v[14:15] op_sel:[1,0]
	v_mov_b32_e32 v17, v15
	s_waitcnt vmcnt(11)
	v_mul_f32_e32 v66, v31, v31
	v_mul_f32_e32 v82, v33, v33
	v_pk_add_f32 v[12:13], v[84:85], v[12:13]
	v_pk_add_f32 v[10:11], v[10:11], v[16:17]
	v_mul_f32_e32 v89, v22, v22
	v_mul_f32_e32 v90, v23, v23
	v_mul_f32_e32 v91, v24, v24
	v_mul_f32_e32 v92, v25, v25
	v_pk_fma_f32 v[14:15], v[30:31], v[30:31], v[66:67] op_sel_hi:[1,1,0]
	v_pk_fma_f32 v[66:67], v[32:33], v[32:33], v[82:83] op_sel_hi:[1,1,0]
	v_pk_add_f32 v[12:13], v[12:13], v[12:13] op_sel:[0,1] op_sel_hi:[1,0]
	v_pk_add_f32 v[10:11], v[10:11], v[10:11] op_sel:[0,1] op_sel_hi:[1,0]
	v_mov_b32_e32 v15, v91
	v_mov_b32_e32 v67, v92
	v_mov_b32_e32 v13, v89
	v_mov_b32_e32 v11, v90
	v_pk_add_f32 v[14:15], v[14:15], v[66:67]
	v_pk_add_f32 v[10:11], v[12:13], v[10:11]
	v_cndmask_b32_e32 v82, v35, v83, vcc
	v_pk_add_f32 v[10:11], v[10:11], v[14:15]
	v_lshlrev_b32_e32 v166, 2, v82
	v_add_f32_e32 v66, v10, v11
	global_load_dwordx4 v[10:13], v54, s[8:9] offset:2064
	global_load_dwordx4 v[14:17], v54, s[8:9] offset:2048
	ds_bpermute_b32 v67, v165, v66
	s_waitcnt vmcnt(12)
	v_pk_add_f32 v[82:83], v[38:39], 1.0 op_sel_hi:[1,0]
	v_cmp_lt_i32_e32 vcc, v86, v87
	s_waitcnt vmcnt(11)
	v_pk_add_f32 v[44:45], v[44:45], 1.0 op_sel_hi:[1,0]
	s_waitcnt vmcnt(9)
	v_pk_add_f32 v[52:53], v[52:53], 1.0 op_sel_hi:[1,0]
	s_waitcnt lgkmcnt(0)
	v_add_f32_e32 v66, v66, v67
	ds_bpermute_b32 v67, v169, v66
	v_pk_add_f32 v[42:43], v[42:43], 1.0 op_sel_hi:[1,0]
	v_pk_add_f32 v[50:51], v[50:51], 1.0 op_sel_hi:[1,0]
	v_pk_add_f32 v[84:85], v[48:49], 1.0 op_sel_hi:[1,0]
	s_waitcnt vmcnt(5)
	v_pk_mul_f32 v[48:49], v[78:79], v[50:51]
	s_waitcnt lgkmcnt(0)
	v_add_f32_e32 v55, v66, v67
	ds_bpermute_b32 v66, v168, v55
	v_cndmask_b32_e32 v67, v35, v86, vcc
	v_lshlrev_b32_e32 v164, 2, v67
	v_pk_add_f32 v[86:87], v[46:47], 1.0 op_sel_hi:[1,0]
	v_pk_mul_f32 v[50:51], v[76:77], v[84:85]
	s_waitcnt lgkmcnt(0)
	v_add_f32_e32 v55, v55, v66
	ds_bpermute_b32 v73, v167, v55
	v_pk_add_f32 v[66:67], v[40:41], 1.0 op_sel_hi:[1,0]
	v_pk_mul_f32 v[40:41], v[62:63], v[42:43]
	v_pk_mul_f32 v[42:43], v[60:61], v[66:67]
	v_cmp_eq_u32_e64 s[8:9], 3, v1
	s_waitcnt lgkmcnt(0)
	v_add_f32_e32 v38, v55, v73
	ds_bpermute_b32 v39, v166, v38
	s_waitcnt lgkmcnt(0)
	v_add_f32_e32 v46, v38, v39
	ds_bpermute_b32 v47, v164, v46
	v_pk_mul_f32 v[38:39], v[64:65], v[44:45]
	v_pk_mul_f32 v[44:45], v[58:59], v[82:83]
	s_waitcnt lgkmcnt(0)
; #define GAS __attribute__((address_space(1)))
; #define LAS __attribute__((address_space(3)))
; __device__ __forceinline__ unsigned pk2(float lo, float hi) { return pg8::cvt_pk_bf16(lo, hi); }
; template <int LO, int HI> __global__ void __launch_bounds__(NWAVES * 64, 2) fox_fwd(Args args) {
;     ...
;             const float rstd = 1.0f / sqrtf(wave_sum(s2) * (1.0f / D) + EPS);
; #pragma unroll
;             for (int j = 0; j < 4; ++j) v[j] = v[j] * rstd * gm[j] + sh[j];
; #pragma unroll
;             for (int j = 0; j < 2; ++j) { v4u o; o.x = pk2(v[2 * j][0], v[2 * j][1]); o.y = pk2(v[2 * j][2], v[2 * j][3]); o.z = pk2(v[2 * j + 1][0], v[2 * j + 1][1]); o.w = pk2(v[2 * j + 1][2], v[2 * j + 1][3]);
;                 *(GAS v4u*)(HB + (size_t)m * D + 8 * lane + 512 * j) = o; }
;             float fl[8];
; #pragma unroll
;             for (int q = 0; q < 8; ++q) { float a = 0.f;
; #pragma unroll
;                 for (int j = 0; j < 4; ++j) { const f32x4 w = *(const LAS f32x4*)(wf + q * 1024 + P1COL(j)); a += (v[j][0] * w[0] + v[j][1] * w[1]) + (v[j][2] * w[2] + v[j][3] * w[3]); }
;                 fl[q] = wave_sum(a); }
	v_add_f32_e32 v46, v46, v47
	v_fmamk_f32 v46, v46, 0x3a800000, v69
	v_mul_f32_e32 v47, 0x4f800000, v46
	v_cmp_gt_f32_e32 vcc, s45, v46
	s_nop 1
	v_cndmask_b32_e32 v55, v46, v47, vcc
	v_sqrt_f32_e32 v58, v55
	v_pk_mul_f32 v[46:47], v[80:81], v[52:53]
	v_add_u32_e32 v52, -1, v58
	v_add_u32_e32 v53, 1, v58
	v_fma_f32 v59, -v52, v58, v55
	v_fma_f32 v60, -v53, v58, v55
	v_cmp_ge_f32_e64 s[4:5], 0, v59
	s_nop 1
	v_cndmask_b32_e64 v52, v58, v52, s[4:5]
	v_cmp_lt_f32_e64 s[4:5], 0, v60
	s_nop 1
	v_cndmask_b32_e64 v52, v52, v53, s[4:5]
	v_mul_f32_e32 v53, 0x37800000, v52
	v_cndmask_b32_e32 v52, v52, v53, vcc
	v_cmp_class_f32_e32 vcc, v55, v70
	s_nop 1
	v_cndmask_b32_e32 v55, v52, v55, vcc
	v_div_scale_f32 v58, s[4:5], v55, v55, 1.0
	v_rcp_f32_e32 v59, v58
	v_div_scale_f32 v60, vcc, 1.0, v55, 1.0
	v_pk_mul_f32 v[52:53], v[74:75], v[86:87]
	v_fma_f32 v61, -v58, v59, 1.0
	v_fmac_f32_e32 v59, v61, v59
	v_mul_f32_e32 v61, v60, v59
	v_fma_f32 v62, -v58, v61, v60
	v_fmac_f32_e32 v61, v62, v59
	v_fma_f32 v58, -v58, v61, v60
	v_div_fmas_f32 v58, v58, v59, v61
	v_div_fixup_f32 v64, v58, v55, 1.0
	v_pk_mul_f32 v[18:19], v[64:65], v[18:19] op_sel_hi:[0,1]
	v_pk_mul_f32 v[20:21], v[64:65], v[20:21] op_sel_hi:[0,1]
	s_waitcnt vmcnt(3)
	v_pk_fma_f32 v[60:61], v[42:43], v[20:21], v[4:5]
	v_pk_fma_f32 v[62:63], v[44:45], v[18:19], v[2:3]
	v_pk_mul_f32 v[18:19], v[64:65], v[30:31] op_sel_hi:[0,1]
	v_pk_mul_f32 v[20:21], v[64:65], v[32:33] op_sel_hi:[0,1]
	v_pk_mul_f32 v[58:59], v[64:65], v[26:27] op_sel_hi:[0,1]
	v_pk_mul_f32 v[26:27], v[64:65], v[28:29] op_sel_hi:[0,1]
	s_waitcnt vmcnt(0)
	v_pk_fma_f32 v[28:29], v[46:47], v[20:21], v[16:17]
	v_pk_fma_f32 v[30:31], v[48:49], v[18:19], v[14:15]
	v_pk_mul_f32 v[18:19], v[64:65], v[22:23] op_sel_hi:[0,1]
	v_pk_mul_f32 v[20:21], v[64:65], v[24:25] op_sel_hi:[0,1]
	v_pk_fma_f32 v[26:27], v[38:39], v[26:27], v[8:9]
	v_pk_fma_f32 v[58:59], v[40:41], v[58:59], v[6:7]
	v_pk_fma_f32 v[22:23], v[50:51], v[20:21], v[12:13]
	v_pk_fma_f32 v[24:25], v[52:53], v[18:19], v[10:11]
	v_lshl_add_u64 v[32:33], v[56:57], 0, s[34:35]
	v_cvt_pk_bf16_f32 v18, v58, v59
	v_cvt_pk_bf16_f32 v19, v26, v27
	v_cvt_pk_bf16_f32 v20, v62, v63
	v_cvt_pk_bf16_f32 v21, v60, v61
	global_store_dwordx4 v[32:33], v[18:21], off
	s_lshl_b64 s[4:5], s[36:37], 12
	s_add_u32 s4, s6, s4
	v_cvt_pk_bf16_f32 v18, v30, v31
	v_cvt_pk_bf16_f32 v19, v28, v29
	v_cvt_pk_bf16_f32 v20, v24, v25
	v_cvt_pk_bf16_f32 v21, v22, v23
	ds_read_b128 v[64:67], v72
	ds_read_b128 v[74:77], v72 offset:16
	global_store_dwordx4 v[32:33], v[18:21], off offset:1024
	ds_read_b128 v[18:21], v72 offset:12288
	s_addc_u32 s5, s7, s5
	s_waitcnt lgkmcnt(2)
	v_mul_f32_e32 v55, v59, v65
	v_fmac_f32_e32 v55, v58, v64
	v_mul_f32_e32 v64, v27, v67
	v_fmac_f32_e32 v64, v26, v66
	v_add_f32_e32 v55, v55, v64
	ds_read_b128 v[64:67], v72 offset:2048
	s_waitcnt lgkmcnt(2)
	v_mul_f32_e32 v73, v63, v75
	v_fmac_f32_e32 v73, v62, v74
	v_mul_f32_e32 v74, v61, v77
	v_fmac_f32_e32 v74, v60, v76
	v_add_f32_e32 v73, v73, v74
	ds_read_b128 v[74:77], v72 offset:2064
	s_waitcnt lgkmcnt(1)
	v_mul_f32_e32 v65, v31, v65
	v_fmac_f32_e32 v65, v30, v64
	v_mul_f32_e32 v64, v29, v67
	v_add_f32_e32 v55, 0, v55
	v_fmac_f32_e32 v64, v28, v66
	v_add_f32_e32 v55, v55, v73
	v_add_f32_e32 v64, v65, v64
	v_add_f32_e32 v55, v55, v64
	s_waitcnt lgkmcnt(0)
	v_mul_f32_e32 v64, v25, v75
	v_mul_f32_e32 v65, v23, v77
	v_fmac_f32_e32 v64, v24, v74
	v_fmac_f32_e32 v65, v22, v76
	v_add_f32_e32 v64, v64, v65
	v_add_f32_e32 v55, v55, v64
	ds_bpermute_b32 v64, v165, v55
	ds_read_b128 v[74:77], v72 offset:4112
	v_cmp_eq_u32_e64 s[6:7], 2, v1
	s_waitcnt lgkmcnt(1)
	v_add_f32_e32 v55, v55, v64
	ds_bpermute_b32 v64, v169, v55
	s_waitcnt lgkmcnt(1)
	v_mul_f32_e32 v75, v63, v75
	v_fmac_f32_e32 v75, v62, v74
	v_mul_f32_e32 v74, v61, v77
	v_fmac_f32_e32 v74, v60, v76
	s_waitcnt lgkmcnt(0)
	v_add_f32_e32 v55, v55, v64
	ds_read_b128 v[64:67], v72 offset:4096
	v_add_f32_e32 v74, v75, v74
	ds_bpermute_b32 v73, v168, v55
	s_waitcnt lgkmcnt(1)
	v_mul_f32_e32 v65, v59, v65
	v_fmac_f32_e32 v65, v58, v64
	v_mul_f32_e32 v64, v27, v67
	v_fmac_f32_e32 v64, v26, v66
	v_add_f32_e32 v64, v65, v64
	v_add_f32_e32 v78, 0, v64
	ds_read_b128 v[64:67], v72 offset:6144
	v_add_f32_e32 v78, v78, v74
	ds_read_b128 v[74:77], v72 offset:6160
	s_waitcnt lgkmcnt(2)
	v_add_f32_e32 v55, v55, v73
	ds_bpermute_b32 v73, v167, v55
	s_waitcnt lgkmcnt(2)
	v_mul_f32_e32 v65, v31, v65
	v_fmac_f32_e32 v65, v30, v64
	v_mul_f32_e32 v64, v29, v67
	v_fmac_f32_e32 v64, v28, v66
	v_add_f32_e32 v64, v65, v64
	s_waitcnt lgkmcnt(1)
	v_mul_f32_e32 v65, v25, v75
	v_mul_f32_e32 v66, v23, v77
	v_fmac_f32_e32 v65, v24, v74
	v_fmac_f32_e32 v66, v22, v76
	v_add_f32_e32 v64, v78, v64
	v_add_f32_e32 v65, v65, v66
	v_add_f32_e32 v64, v64, v65
	ds_bpermute_b32 v65, v165, v64
	s_waitcnt lgkmcnt(1)
	v_add_f32_e32 v55, v55, v73
	ds_bpermute_b32 v74, v166, v55
	v_lshlrev_b32_e32 v73, 3, v1
	s_waitcnt lgkmcnt(1)
	v_add_f32_e32 v75, v64, v65
	ds_bpermute_b32 v76, v169, v75
	ds_read_b128 v[64:67], v72 offset:8192
	s_waitcnt lgkmcnt(2)
	v_add_f32_e32 v55, v55, v74
	s_waitcnt lgkmcnt(1)
	v_add_f32_e32 v78, v75, v76
	ds_read_b128 v[74:77], v72 offset:8208
	s_waitcnt lgkmcnt(1)
	v_mul_f32_e32 v65, v59, v65
	v_fmac_f32_e32 v65, v58, v64
	v_mul_f32_e32 v64, v27, v67
	v_fmac_f32_e32 v64, v26, v66
	v_add_f32_e32 v64, v65, v64
	s_waitcnt lgkmcnt(0)
	v_mul_f32_e32 v75, v63, v75
	v_add_f32_e32 v80, 0, v64
	v_fmac_f32_e32 v75, v62, v74
	v_mul_f32_e32 v74, v61, v77
	ds_read_b128 v[64:67], v72 offset:10240
	v_fmac_f32_e32 v74, v60, v76
	v_add_f32_e32 v74, v75, v74
	v_add_f32_e32 v80, v80, v74
	ds_read_b128 v[74:77], v72 offset:10256
	s_waitcnt lgkmcnt(1)
; #define GAS __attribute__((address_space(1)))
; #define LAS __attribute__((address_space(3)))
; __device__ __forceinline__ unsigned pk2(float lo, float hi) { return pg8::cvt_pk_bf16(lo, hi); }
; template <int LO, int HI> __global__ void __launch_bounds__(NWAVES * 64, 2) fox_fwd(Args args) {
;     ...
;         for (int r = 0; r < 16; ++r) { const int m = m0 + r;
;             const GAS float* xr = (const GAS float*)(x + (size_t)m * D);
;             f32x4 v[4]; float s2 = 0.f;
; #pragma unroll
;             for (int j = 0; j < 4; ++j) { v[j] = *(const GAS f32x4*)(xr + P1COL(j)); s2 += (v[j][0] * v[j][0] + v[j][1] * v[j][1]) + (v[j][2] * v[j][2] + v[j][3] * v[j][3]); }
;             const float rstd = 1.0f / sqrtf(wave_sum(s2) * (1.0f / D) + EPS);
; #pragma unroll
;             for (int j = 0; j < 4; ++j) v[j] = v[j] * rstd * gm[j] + sh[j];
; #pragma unroll
;             for (int j = 0; j < 2; ++j) { v4u o; o.x = pk2(v[2 * j][0], v[2 * j][1]); o.y = pk2(v[2 * j][2], v[2 * j][3]); o.z = pk2(v[2 * j + 1][0], v[2 * j + 1][1]); o.w = pk2(v[2 * j + 1][2], v[2 * j + 1][3]);
;                 *(GAS v4u*)(HB + (size_t)m * D + 8 * lane + 512 * j) = o; }
;             float fl[8];
; #pragma unroll
;             for (int q = 0; q < 8; ++q) { float a = 0.f;
; #pragma unroll
;                 for (int j = 0; j < 4; ++j) { const f32x4 w = *(const LAS f32x4*)(wf + q * 1024 + P1COL(j)); a += (v[j][0] * w[0] + v[j][1] * w[1]) + (v[j][2] * w[2] + v[j][3] * w[3]); }
;                 fl[q] = wave_sum(a); }
	v_mul_f32_e32 v65, v31, v65
	ds_bpermute_b32 v79, v168, v78
	v_fmac_f32_e32 v65, v30, v64
	v_mul_f32_e32 v64, v29, v67
	v_fmac_f32_e32 v64, v28, v66
	v_add_f32_e32 v64, v65, v64
	s_waitcnt lgkmcnt(1)
	v_mul_f32_e32 v65, v25, v75
	v_mul_f32_e32 v66, v23, v77
	v_fmac_f32_e32 v65, v24, v74
	v_fmac_f32_e32 v66, v22, v76
	v_add_f32_e32 v64, v80, v64
	v_add_f32_e32 v65, v65, v66
	v_add_f32_e32 v64, v64, v65
	s_waitcnt lgkmcnt(0)
	v_add_f32_e32 v67, v78, v79
	ds_bpermute_b32 v65, v165, v64
	ds_bpermute_b32 v66, v164, v55
	ds_bpermute_b32 v74, v167, v67
	s_waitcnt lgkmcnt(2)
	v_add_f32_e32 v32, v64, v65
	s_waitcnt lgkmcnt(1)
	v_add_f32_e32 v55, v55, v66
	s_waitcnt lgkmcnt(0)
	v_add_f32_e32 v74, v67, v74
	ds_read_b128 v[64:67], v72 offset:12304
	v_mul_f32_e32 v19, v59, v19
	v_fmac_f32_e32 v19, v58, v18
	v_mul_f32_e32 v18, v27, v21
	v_fmac_f32_e32 v18, v26, v20
	v_add_f32_e32 v18, v19, v18
	s_waitcnt lgkmcnt(0)
	v_mul_f32_e32 v65, v63, v65
	v_add_f32_e32 v76, 0, v18
	v_fmac_f32_e32 v65, v62, v64
	v_mul_f32_e32 v64, v61, v67
	ds_read_b128 v[18:21], v72 offset:14336
	v_fmac_f32_e32 v64, v60, v66
	v_add_f32_e32 v64, v65, v64
	v_add_f32_e32 v76, v76, v64
	ds_read_b128 v[64:67], v72 offset:14352
	s_waitcnt lgkmcnt(1)
	v_mul_f32_e32 v19, v31, v19
	v_fmac_f32_e32 v19, v30, v18
	v_mul_f32_e32 v18, v29, v21
	v_fmac_f32_e32 v18, v28, v20
	v_add_f32_e32 v18, v19, v18
	s_waitcnt lgkmcnt(0)
	v_mul_f32_e32 v19, v25, v65
	v_mul_f32_e32 v20, v23, v67
	v_fmac_f32_e32 v19, v24, v64
	v_fmac_f32_e32 v20, v22, v66
	v_add_f32_e32 v18, v76, v18
	v_add_f32_e32 v19, v19, v20
	v_add_f32_e32 v64, v18, v19
	ds_bpermute_b32 v75, v166, v74
	ds_bpermute_b32 v65, v165, v64
	ds_read_b128 v[18:21], v72 offset:16384
	ds_bpermute_b32 v33, v169, v32
	s_waitcnt lgkmcnt(3)
	v_add_f32_e32 v74, v74, v75
	s_waitcnt lgkmcnt(2)
	v_add_f32_e32 v75, v64, v65
	ds_read_b128 v[64:67], v72 offset:16400
	s_waitcnt lgkmcnt(2)
	v_mul_f32_e32 v19, v59, v19
	v_fmac_f32_e32 v19, v58, v18
	v_mul_f32_e32 v18, v27, v21
	v_fmac_f32_e32 v18, v26, v20
	v_add_f32_e32 v18, v19, v18
	s_waitcnt lgkmcnt(0)
	v_mul_f32_e32 v65, v63, v65
	v_add_f32_e32 v77, 0, v18
	v_fmac_f32_e32 v65, v62, v64
	v_mul_f32_e32 v64, v61, v67
	ds_read_b128 v[18:21], v72 offset:18432
	v_fmac_f32_e32 v64, v60, v66
	v_add_f32_e32 v64, v65, v64
	v_add_f32_e32 v32, v32, v33
	v_add_f32_e32 v77, v77, v64
	ds_read_b128 v[64:67], v72 offset:18448
	ds_bpermute_b32 v33, v168, v32
	s_waitcnt lgkmcnt(2)
	v_mul_f32_e32 v19, v31, v19
	v_fmac_f32_e32 v19, v30, v18
	v_mul_f32_e32 v18, v29, v21
	v_fmac_f32_e32 v18, v28, v20
	v_add_f32_e32 v18, v19, v18
	s_waitcnt lgkmcnt(1)
	v_mul_f32_e32 v19, v25, v65
	v_mul_f32_e32 v20, v23, v67
	s_waitcnt lgkmcnt(0)
	v_add_f32_e32 v32, v32, v33
	ds_bpermute_b32 v76, v169, v75
	v_fmac_f32_e32 v19, v24, v64
	v_fmac_f32_e32 v20, v22, v66
	ds_bpermute_b32 v33, v167, v32
	v_add_f32_e32 v18, v77, v18
	v_add_f32_e32 v19, v19, v20
	v_add_f32_e32 v18, v18, v19
	ds_bpermute_b32 v19, v165, v18
	s_waitcnt lgkmcnt(2)
	v_add_f32_e32 v21, v75, v76
	s_waitcnt lgkmcnt(1)
	v_add_f32_e32 v20, v32, v33
	ds_bpermute_b32 v32, v168, v21
	ds_bpermute_b32 v33, v166, v20
	s_waitcnt lgkmcnt(2)
	v_add_f32_e32 v18, v18, v19
	ds_bpermute_b32 v19, v169, v18
	ds_bpermute_b32 v64, v164, v74
	s_waitcnt lgkmcnt(3)
	v_add_f32_e32 v21, v21, v32
	ds_bpermute_b32 v32, v167, v21
	s_waitcnt lgkmcnt(3)
	v_add_f32_e32 v20, v20, v33
	s_waitcnt lgkmcnt(2)
	v_add_f32_e32 v18, v18, v19
	ds_bpermute_b32 v19, v168, v18
	ds_bpermute_b32 v33, v164, v20
	s_waitcnt lgkmcnt(2)
	v_add_f32_e32 v21, v21, v32
	ds_bpermute_b32 v32, v166, v21
	v_add_f32_e32 v74, v74, v64
	s_waitcnt lgkmcnt(2)
	v_add_f32_e32 v64, v18, v19
	ds_bpermute_b32 v65, v167, v64
	s_waitcnt lgkmcnt(2)
	v_add_f32_e32 v75, v20, v33
	s_waitcnt lgkmcnt(1)
	v_add_f32_e32 v32, v21, v32
	ds_read_b128 v[18:21], v72 offset:20480
	ds_bpermute_b32 v33, v164, v32
	s_waitcnt lgkmcnt(2)
	v_add_f32_e32 v76, v64, v65
	ds_read_b128 v[64:67], v72 offset:20496
	ds_bpermute_b32 v77, v166, v76
	s_waitcnt lgkmcnt(3)
	v_mul_f32_e32 v19, v59, v19
	v_fmac_f32_e32 v19, v58, v18
	v_mul_f32_e32 v18, v27, v21
	v_fmac_f32_e32 v18, v26, v20
	v_add_f32_e32 v18, v19, v18
	s_waitcnt lgkmcnt(1)
	v_mul_f32_e32 v65, v63, v65
	v_add_f32_e32 v78, 0, v18
	v_fmac_f32_e32 v65, v62, v64
	v_mul_f32_e32 v64, v61, v67
	ds_read_b128 v[18:21], v72 offset:22528
	v_fmac_f32_e32 v64, v60, v66
	v_add_f32_e32 v64, v65, v64
	v_add_f32_e32 v78, v78, v64
	ds_read_b128 v[64:67], v72 offset:22544
	s_waitcnt lgkmcnt(1)
	v_mul_f32_e32 v19, v31, v19
	v_fmac_f32_e32 v19, v30, v18
	v_mul_f32_e32 v18, v29, v21
	v_fmac_f32_e32 v18, v28, v20
	v_add_f32_e32 v18, v19, v18
	s_waitcnt lgkmcnt(0)
	v_mul_f32_e32 v19, v25, v65
	v_mul_f32_e32 v20, v23, v67
	v_fmac_f32_e32 v19, v24, v64
	v_fmac_f32_e32 v20, v22, v66
	v_add_f32_e32 v18, v78, v18
	v_add_f32_e32 v19, v19, v20
	v_add_f32_e32 v64, v18, v19
	ds_bpermute_b32 v65, v165, v64
	ds_read_b128 v[18:21], v72 offset:24576
	v_add_f32_e32 v92, v32, v33
	v_add_f32_e32 v93, v76, v77
	ds_bpermute_b32 v94, v164, v93
	s_waitcnt lgkmcnt(2)
	v_add_f32_e32 v95, v64, v65
	ds_read_b128 v[64:67], v72 offset:24592
	s_waitcnt lgkmcnt(2)
	v_pk_mul_f32 v[18:19], v[58:59], v[18:19]
	v_pk_mul_f32 v[20:21], v[26:27], v[20:21]
	ds_bpermute_b32 v96, v169, v95
	v_pk_mov_b32 v[32:33], v[18:19], v[20:21] op_sel:[1,0]
	v_mov_b32_e32 v19, v21
	v_pk_add_f32 v[18:19], v[32:33], v[18:19]
	s_waitcnt lgkmcnt(1)
	v_pk_mul_f32 v[64:65], v[62:63], v[64:65]
	v_add_f32_e32 v18, v18, v19
	v_add_f32_e32 v32, 0, v18
	ds_read_b128 v[18:21], v72 offset:26624
	ds_read_b128 v[76:79], v72 offset:26640
	global_load_dwordx4 v[80:83], v54, s[4:5] offset:16
	global_load_dwordx4 v[84:87], v54, s[4:5]
	v_pk_mul_f32 v[66:67], v[60:61], v[66:67]
	s_waitcnt lgkmcnt(0)
; #define GAS __attribute__((address_space(1)))
; #define LAS __attribute__((address_space(3)))
; __device__ __forceinline__ unsigned pk2(float lo, float hi) { return pg8::cvt_pk_bf16(lo, hi); }
; template <int LO, int HI> __global__ void __launch_bounds__(NWAVES * 64, 2) fox_fwd(Args args) {
;     ...
;             f32x4 v[4]; float s2 = 0.f;
; #pragma unroll
;             for (int j = 0; j < 4; ++j) { v[j] = *(const GAS f32x4*)(xr + P1COL(j)); s2 += (v[j][0] * v[j][0] + v[j][1] * v[j][1]) + (v[j][2] * v[j][2] + v[j][3] * v[j][3]); }
;             const float rstd = 1.0f / sqrtf(wave_sum(s2) * (1.0f / D) + EPS);
; #pragma unroll
;             for (int j = 0; j < 4; ++j) v[j] = v[j] * rstd * gm[j] + sh[j];
; #pragma unroll
;             for (int j = 0; j < 2; ++j) { v4u o; o.x = pk2(v[2 * j][0], v[2 * j][1]); o.y = pk2(v[2 * j][2], v[2 * j][3]); o.z = pk2(v[2 * j + 1][0], v[2 * j + 1][1]); o.w = pk2(v[2 * j + 1][2], v[2 * j + 1][3]);
;                 *(GAS v4u*)(HB + (size_t)m * D + 8 * lane + 512 * j) = o; }
;             float fl[8];
; #pragma unroll
;             for (int q = 0; q < 8; ++q) { float a = 0.f;
; #pragma unroll
;                 for (int j = 0; j < 4; ++j) { const f32x4 w = *(const LAS f32x4*)(wf + q * 1024 + P1COL(j)); a += (v[j][0] * w[0] + v[j][1] * w[1]) + (v[j][2] * w[2] + v[j][3] * w[3]); }
;                 fl[q] = wave_sum(a); }
;             float mine = fl[0];
; #pragma unroll
;             for (int q = 1; q < 8; ++q) mine = (lane == q) ? fl[q] : mine;
;             { const float z = mine + bfv; const float ls = fminf(z, 0.f) - log1pf(__expf(-fabsf(z)));
	v_mul_f32_e32 v33, v24, v76
	v_pk_mov_b32 v[88:89], v[64:65], v[66:67] op_sel:[1,0]
	v_mov_b32_e32 v65, v67
	v_pk_add_f32 v[64:65], v[88:89], v[64:65]
	v_mul_f32_e32 v66, v25, v77
	v_mul_f32_e32 v67, v22, v78
	v_mul_f32_e32 v97, v23, v79
	global_load_dwordx4 v[76:79], v54, s[4:5] offset:2048
	global_load_dwordx4 v[88:91], v54, s[4:5] offset:2064
	v_pk_add_f32 v[64:65], v[64:65], v[64:65] op_sel:[0,1] op_sel_hi:[1,0]
	v_cmp_eq_u32_e64 s[4:5], 1, v1
	v_mov_b32_e32 v65, v66
	v_pk_add_f32 v[32:33], v[32:33], v[64:65]
	v_mul_f32_e32 v64, v31, v19
	v_pk_fma_f32 v[18:19], v[30:31], v[18:19], v[64:65] op_sel_hi:[1,1,0]
	v_mul_f32_e32 v64, v29, v21
	v_pk_fma_f32 v[20:21], v[28:29], v[20:21], v[64:65] op_sel_hi:[1,1,0]
	v_mov_b32_e32 v19, v67
	v_mov_b32_e32 v21, v97
	v_pk_add_f32 v[64:65], v[18:19], v[20:21]
	ds_read_b128 v[18:21], v72 offset:28672
	v_pk_add_f32 v[32:33], v[32:33], v[64:65]
	ds_read_b128 v[64:67], v72 offset:28688
	v_add_f32_e32 v97, v32, v33
	ds_bpermute_b32 v98, v165, v97
	s_waitcnt lgkmcnt(2)
	v_pk_mul_f32 v[18:19], v[58:59], v[18:19]
	v_pk_mul_f32 v[20:21], v[26:27], v[20:21]
	s_waitcnt lgkmcnt(1)
	v_pk_mul_f32 v[32:33], v[62:63], v[64:65]
	v_pk_mov_b32 v[26:27], v[18:19], v[20:21] op_sel:[1,0]
	v_mov_b32_e32 v19, v21
	v_pk_add_f32 v[18:19], v[26:27], v[18:19]
	v_pk_mul_f32 v[58:59], v[60:61], v[66:67]
	v_add_f32_e32 v18, v18, v19
	v_add_f32_e32 v26, 0, v18
	ds_read_b128 v[18:21], v72 offset:30720
	ds_read_b128 v[62:65], v72 offset:30736
	v_pk_mov_b32 v[60:61], v[32:33], v[58:59] op_sel:[1,0]
	v_mov_b32_e32 v33, v59
	v_pk_add_f32 v[32:33], v[60:61], v[32:33]
	s_waitcnt lgkmcnt(0)
	v_mul_f32_e32 v27, v24, v62
	v_mul_f32_e32 v24, v25, v63
	v_mul_f32_e32 v25, v22, v64
	v_mul_f32_e32 v58, v23, v65
	v_pk_add_f32 v[22:23], v[32:33], v[32:33] op_sel:[0,1] op_sel_hi:[1,0]
	s_nop 0
	v_mov_b32_e32 v23, v24
	v_mul_f32_e32 v24, v31, v19
	v_pk_fma_f32 v[18:19], v[30:31], v[18:19], v[24:25] op_sel_hi:[1,1,0]
	v_mul_f32_e32 v24, v29, v21
	v_pk_fma_f32 v[20:21], v[28:29], v[20:21], v[24:25] op_sel_hi:[1,1,0]
	v_mov_b32_e32 v19, v25
	v_mov_b32_e32 v21, v58
	v_pk_add_f32 v[22:23], v[26:27], v[22:23]
	v_pk_add_f32 v[18:19], v[18:19], v[20:21]
	v_add_f32_e32 v20, v95, v96
	v_pk_add_f32 v[18:19], v[22:23], v[18:19]
	ds_bpermute_b32 v21, v168, v20
	v_add_f32_e32 v18, v18, v19
	ds_bpermute_b32 v19, v165, v18
	v_add_f32_e32 v22, v97, v98
	ds_bpermute_b32 v23, v169, v22
	s_waitcnt lgkmcnt(2)
	v_add_f32_e32 v20, v20, v21
	ds_bpermute_b32 v21, v167, v20
	s_waitcnt lgkmcnt(2)
	v_add_f32_e32 v18, v18, v19
	ds_bpermute_b32 v19, v169, v18
	s_waitcnt lgkmcnt(2)
	v_add_f32_e32 v22, v22, v23
	ds_bpermute_b32 v23, v168, v22
	s_waitcnt lgkmcnt(2)
	v_add_f32_e32 v20, v20, v21
	ds_bpermute_b32 v21, v166, v20
	s_waitcnt lgkmcnt(2)
	v_add_f32_e32 v18, v18, v19
	ds_bpermute_b32 v19, v168, v18
	s_waitcnt lgkmcnt(2)
	v_add_f32_e32 v22, v22, v23
	ds_bpermute_b32 v23, v167, v22
	s_waitcnt lgkmcnt(2)
	v_add_f32_e32 v26, v20, v21
	ds_bpermute_b32 v27, v164, v26
	s_waitcnt lgkmcnt(2)
	v_add_f32_e32 v18, v18, v19
	ds_bpermute_b32 v19, v167, v18
	s_waitcnt vmcnt(2)
	v_pk_mul_f32 v[20:21], v[84:85], v[84:85]
	s_waitcnt lgkmcnt(2)
	v_add_f32_e32 v28, v22, v23
	ds_bpermute_b32 v29, v166, v28
	s_waitcnt lgkmcnt(1)
	v_add_f32_e32 v30, v18, v19
	v_pk_mul_f32 v[18:19], v[86:87], v[86:87]
	ds_bpermute_b32 v31, v166, v30
	v_pk_mov_b32 v[22:23], v[20:21], v[18:19] op_sel:[1,0]
	v_mov_b32_e32 v21, v19
	v_pk_add_f32 v[18:19], v[22:23], v[20:21]
	v_pk_mul_f32 v[20:21], v[82:83], v[82:83]
	v_pk_mul_f32 v[22:23], v[80:81], v[80:81]
	v_pk_add_f32 v[18:19], v[18:19], v[18:19] op_sel:[0,1] op_sel_hi:[1,0]
	v_pk_mov_b32 v[24:25], v[22:23], v[20:21] op_sel:[1,0]
	v_mov_b32_e32 v23, v21
	v_pk_add_f32 v[20:21], v[24:25], v[22:23]
	s_waitcnt vmcnt(0)
	v_mul_f32_e32 v22, v88, v88
	v_mul_f32_e32 v23, v89, v89
	v_pk_add_f32 v[20:21], v[20:21], v[20:21] op_sel:[0,1] op_sel_hi:[1,0]
	v_mov_b32_e32 v19, v22
	v_mov_b32_e32 v21, v23
	v_pk_add_f32 v[18:19], v[18:19], v[20:21]
	v_mul_f32_e32 v20, v77, v77
	v_mul_f32_e32 v22, v79, v79
	v_mul_f32_e32 v24, v90, v90
	v_mul_f32_e32 v25, v91, v91
	v_pk_fma_f32 v[20:21], v[76:77], v[76:77], v[20:21] op_sel_hi:[1,1,0]
	v_pk_fma_f32 v[22:23], v[78:79], v[78:79], v[22:23] op_sel_hi:[1,1,0]
	v_mov_b32_e32 v21, v24
	v_mov_b32_e32 v23, v25
	v_pk_add_f32 v[20:21], v[20:21], v[22:23]
	s_waitcnt lgkmcnt(0)
	v_add_f32_e32 v22, v30, v31
	v_pk_add_f32 v[18:19], v[18:19], v[20:21]
	v_add_f32_e32 v20, v28, v29
	v_add_f32_e32 v18, v18, v19
	ds_bpermute_b32 v19, v165, v18
	ds_bpermute_b32 v21, v164, v20
	ds_bpermute_b32 v23, v164, v22
	v_add_f32_e32 v24, v93, v94
	v_add_f32_e32 v25, v26, v27
	s_waitcnt lgkmcnt(2)
	v_add_f32_e32 v18, v18, v19
	ds_bpermute_b32 v19, v169, v18
	s_waitcnt lgkmcnt(2)
	v_add_f32_e32 v20, v20, v21
	s_waitcnt lgkmcnt(1)
	v_add_f32_e32 v21, v22, v23
	v_cndmask_b32_e64 v22, v55, v74, s[4:5]
	v_cndmask_b32_e64 v22, v22, v75, s[6:7]
	s_waitcnt lgkmcnt(0)
	v_add_f32_e32 v18, v18, v19
	ds_bpermute_b32 v19, v168, v18
	v_cndmask_b32_e64 v22, v22, v92, s[8:9]
	v_cndmask_b32_e64 v22, v22, v24, s[10:11]
	v_cndmask_b32_e64 v22, v22, v25, s[12:13]
	v_cndmask_b32_e64 v20, v22, v20, s[14:15]
	s_waitcnt lgkmcnt(0)
	v_add_f32_e32 v18, v18, v19
	ds_bpermute_b32 v19, v167, v18
	v_cndmask_b32_e64 v20, v20, v21, s[16:17]
	v_add_f32_e32 v20, v71, v20
	v_min_f32_e32 v22, 0, v20
	v_mul_f32_e64 v20, |v20|, s29
	s_waitcnt lgkmcnt(0)
	v_add_f32_e32 v18, v18, v19
	ds_bpermute_b32 v19, v166, v18
	v_exp_f32_e32 v55, v20
	s_waitcnt lgkmcnt(0)
	v_add_f32_e32 v18, v18, v19
	ds_bpermute_b32 v19, v164, v18
	v_add_f32_e32 v92, 1.0, v55
	v_add_f32_e32 v23, -1.0, v92
	v_sub_f32_e32 v26, v23, v92
	v_add_f32_e32 v26, 1.0, v26
	s_waitcnt lgkmcnt(0)
; #define GAS __attribute__((address_space(1)))
; #define LAS __attribute__((address_space(3)))
; __device__ __forceinline__ unsigned pk2(float lo, float hi) { return pg8::cvt_pk_bf16(lo, hi); }
; template <int LO, int HI> __global__ void __launch_bounds__(NWAVES * 64, 2) fox_fwd(Args args) {
;     ...
;             const float rstd = 1.0f / sqrtf(wave_sum(s2) * (1.0f / D) + EPS);
; #pragma unroll
;             for (int j = 0; j < 4; ++j) v[j] = v[j] * rstd * gm[j] + sh[j];
; #pragma unroll
;             for (int j = 0; j < 2; ++j) { v4u o; o.x = pk2(v[2 * j][0], v[2 * j][1]); o.y = pk2(v[2 * j][2], v[2 * j][3]); o.z = pk2(v[2 * j + 1][0], v[2 * j + 1][1]); o.w = pk2(v[2 * j + 1][2], v[2 * j + 1][3]);
;                 *(GAS v4u*)(HB + (size_t)m * D + 8 * lane + 512 * j) = o; }
;             float fl[8];
; #pragma unroll
;             for (int q = 0; q < 8; ++q) { float a = 0.f;
; #pragma unroll
;                 for (int j = 0; j < 4; ++j) { const f32x4 w = *(const LAS f32x4*)(wf + q * 1024 + P1COL(j)); a += (v[j][0] * w[0] + v[j][1] * w[1]) + (v[j][2] * w[2] + v[j][3] * w[3]); }
;                 fl[q] = wave_sum(a); }
	v_add_f32_e32 v18, v18, v19
	v_fmamk_f32 v18, v18, 0x3a800000, v69
	v_mul_f32_e32 v19, 0x4f800000, v18
	v_cmp_gt_f32_e32 vcc, s45, v18
	v_sub_f32_e32 v23, v55, v23
	v_add_f32_e32 v23, v23, v26
	v_cndmask_b32_e32 v18, v18, v19, vcc
	v_sqrt_f32_e32 v19, v18
	s_nop 0
	v_add_u32_e32 v20, -1, v19
	v_fma_f32 v21, -v20, v19, v18
	v_cmp_ge_f32_e64 s[20:21], 0, v21
	v_add_u32_e32 v21, 1, v19
	s_nop 0
	v_cndmask_b32_e64 v20, v19, v20, s[20:21]
	v_fma_f32 v19, -v21, v19, v18
	v_cmp_lt_f32_e64 s[20:21], 0, v19
	s_nop 1
	v_cndmask_b32_e64 v19, v20, v21, s[20:21]
	v_mul_f32_e32 v20, 0x37800000, v19
	v_cndmask_b32_e32 v19, v19, v20, vcc
	v_cmp_class_f32_e32 vcc, v18, v70
	s_nop 1
	v_cndmask_b32_e32 v18, v19, v18, vcc
	v_div_scale_f32 v19, s[20:21], v18, v18, 1.0
	v_rcp_f32_e32 v20, v19
	s_lshl_b64 s[20:21], s[36:37], 11
	s_mov_b32 s37, 0x3f2aaaab
	s_mov_b32 s36, 0x3f317218
	v_fma_f32 v21, -v19, v20, 1.0
	v_fmac_f32_e32 v20, v21, v20
	v_div_scale_f32 v21, vcc, 1.0, v18, 1.0
	v_mul_f32_e32 v24, v21, v20
	v_fma_f32 v25, -v19, v24, v21
	v_fmac_f32_e32 v24, v25, v20
	v_fma_f32 v19, -v19, v24, v21
	v_div_fmas_f32 v19, v19, v20, v24
	v_div_fixup_f32 v18, v19, v18, 1.0
	v_pk_mul_f32 v[20:21], v[18:19], v[84:85] op_sel_hi:[0,1]
	v_pk_mul_f32 v[24:25], v[18:19], v[86:87] op_sel_hi:[0,1]
	v_pk_fma_f32 v[64:65], v[40:41], v[20:21], v[6:7]
	v_pk_mul_f32 v[20:21], v[18:19], v[80:81] op_sel_hi:[0,1]
	v_pk_fma_f32 v[62:63], v[38:39], v[24:25], v[8:9]
	v_pk_mul_f32 v[24:25], v[18:19], v[82:83] op_sel_hi:[0,1]
	v_pk_fma_f32 v[66:67], v[44:45], v[20:21], v[2:3]
	v_pk_mul_f32 v[20:21], v[18:19], v[76:77] op_sel_hi:[0,1]
	v_pk_fma_f32 v[32:33], v[42:43], v[24:25], v[4:5]
	v_pk_mul_f32 v[24:25], v[18:19], v[78:79] op_sel_hi:[0,1]
	v_pk_fma_f32 v[30:31], v[48:49], v[20:21], v[14:15]
	v_pk_mul_f32 v[20:21], v[18:19], v[88:89] op_sel_hi:[0,1]
	v_pk_mul_f32 v[18:19], v[18:19], v[90:91] op_sel_hi:[0,1]
	v_pk_fma_f32 v[28:29], v[46:47], v[24:25], v[16:17]
	v_pk_fma_f32 v[58:59], v[50:51], v[18:19], v[12:13]
	v_pk_fma_f32 v[60:61], v[52:53], v[20:21], v[10:11]
	v_lshl_add_u64 v[24:25], v[56:57], 0, s[20:21]
	v_cvt_pk_bf16_f32 v18, v64, v65
	v_cvt_pk_bf16_f32 v19, v62, v63
	v_cvt_pk_bf16_f32 v20, v66, v67
	v_cvt_pk_bf16_f32 v21, v32, v33
	global_store_dwordx4 v[24:25], v[18:21], off
	s_mov_b32 s20, 0x3e9b6dac
	s_nop 0
	v_cvt_pk_bf16_f32 v18, v30, v31
	v_cvt_pk_bf16_f32 v19, v28, v29
	v_cvt_pk_bf16_f32 v20, v60, v61
	v_cvt_pk_bf16_f32 v21, v58, v59
	ds_read_b128 v[74:77], v72
	ds_read_b128 v[78:81], v72 offset:16
	s_waitcnt lgkmcnt(1)
	v_mul_f32_e32 v26, v65, v75
	v_mul_f32_e32 v27, v63, v77
	v_fmac_f32_e32 v26, v64, v74
	v_fmac_f32_e32 v27, v62, v76
	ds_read_b128 v[74:77], v72 offset:2048
	v_add_f32_e32 v26, v26, v27
	s_waitcnt lgkmcnt(1)
	v_mul_f32_e32 v27, v67, v79
	v_mul_f32_e32 v56, v33, v81
	v_fmac_f32_e32 v27, v66, v78
	v_fmac_f32_e32 v56, v32, v80
	ds_read_b128 v[78:81], v72 offset:2064
	v_add_f32_e32 v26, 0, v26
	v_add_f32_e32 v27, v27, v56
	v_add_f32_e32 v26, v26, v27
	s_waitcnt lgkmcnt(1)
	v_mul_f32_e32 v27, v31, v75
	v_mul_f32_e32 v56, v29, v77
	v_fmac_f32_e32 v27, v30, v74
	v_fmac_f32_e32 v56, v28, v76
	v_add_f32_e32 v27, v27, v56
	v_add_f32_e32 v26, v26, v27
	s_waitcnt lgkmcnt(0)
	v_mul_f32_e32 v27, v61, v79
	v_mul_f32_e32 v56, v59, v81
	v_fmac_f32_e32 v27, v60, v78
	v_fmac_f32_e32 v56, v58, v80
	v_add_f32_e32 v27, v27, v56
	v_add_f32_e32 v56, v26, v27
	ds_bpermute_b32 v57, v165, v56
	v_frexp_mant_f32_e32 v74, v92
	v_cmp_gt_f32_e32 vcc, s37, v74
	ds_read_b128 v[74:77], v72 offset:4096
	v_cvt_f64_f32_e32 v[26:27], v92
	s_waitcnt lgkmcnt(1)
	v_add_f32_e32 v57, v56, v57
	ds_bpermute_b32 v78, v169, v57
	v_frexp_exp_i32_f64_e32 v26, v[26:27]
	v_subbrev_co_u32_e32 v56, vcc, 0, v26, vcc
	v_sub_u32_e32 v27, 0, v56
	s_waitcnt lgkmcnt(0)
	v_add_f32_e32 v57, v57, v78
	ds_read_b128 v[78:81], v72 offset:4112
	v_mul_f32_e32 v26, v65, v75
	v_fmac_f32_e32 v26, v64, v74
	v_mul_f32_e32 v74, v63, v77
	v_fmac_f32_e32 v74, v62, v76
	v_add_f32_e32 v26, v26, v74
	s_waitcnt lgkmcnt(0)
	v_mul_f32_e32 v79, v67, v79
	ds_read_b128 v[74:77], v72 offset:6144
	v_fmac_f32_e32 v79, v66, v78
	v_mul_f32_e32 v78, v33, v81
	v_fmac_f32_e32 v78, v32, v80
	v_add_f32_e32 v26, 0, v26
	v_add_f32_e32 v78, v79, v78
	v_add_f32_e32 v26, v26, v78
	ds_read_b128 v[78:81], v72 offset:6160
	s_waitcnt lgkmcnt(1)
	v_mul_f32_e32 v75, v31, v75
	v_fmac_f32_e32 v75, v30, v74
	v_mul_f32_e32 v74, v29, v77
	v_fmac_f32_e32 v74, v28, v76
	v_add_f32_e32 v74, v75, v74
	v_add_f32_e32 v26, v26, v74
	s_waitcnt lgkmcnt(0)
	v_mul_f32_e32 v74, v61, v79
	v_mul_f32_e32 v75, v59, v81
	v_fmac_f32_e32 v74, v60, v78
	v_fmac_f32_e32 v75, v58, v80
	v_add_f32_e32 v74, v74, v75
	v_add_f32_e32 v78, v26, v74
	ds_bpermute_b32 v79, v165, v78
	ds_read_b128 v[74:77], v72 offset:8192
	ds_bpermute_b32 v82, v168, v57
	v_ldexp_f32 v26, v92, v27
	s_waitcnt lgkmcnt(2)
	v_add_f32_e32 v83, v78, v79
	ds_read_b128 v[78:81], v72 offset:8208
	s_waitcnt lgkmcnt(2)
	v_mul_f32_e32 v75, v65, v75
	v_fmac_f32_e32 v75, v64, v74
	v_mul_f32_e32 v74, v63, v77
	v_fmac_f32_e32 v74, v62, v76
	v_add_f32_e32 v74, v75, v74
	s_waitcnt lgkmcnt(0)
	v_mul_f32_e32 v79, v67, v79
	v_add_f32_e32 v85, 0, v74
	v_fmac_f32_e32 v79, v66, v78
	v_mul_f32_e32 v78, v33, v81
	ds_read_b128 v[74:77], v72 offset:10240
	v_fmac_f32_e32 v78, v32, v80
	v_add_f32_e32 v78, v79, v78
	v_add_f32_e32 v85, v85, v78
	ds_read_b128 v[78:81], v72 offset:10256
	s_waitcnt lgkmcnt(1)
	v_mul_f32_e32 v75, v31, v75
	v_fmac_f32_e32 v75, v30, v74
	v_mul_f32_e32 v74, v29, v77
	v_fmac_f32_e32 v74, v28, v76
	v_add_f32_e32 v57, v57, v82
	v_add_f32_e32 v74, v75, v74
	s_waitcnt lgkmcnt(0)
; #define LAS __attribute__((address_space(3)))
; template <int LO, int HI> __global__ void __launch_bounds__(NWAVES * 64, 2) fox_fwd(Args args) {
;     ...
;             for (int q = 0; q < 8; ++q) { float a = 0.f;
; #pragma unroll
;                 for (int j = 0; j < 4; ++j) { const f32x4 w = *(const LAS f32x4*)(wf + q * 1024 + P1COL(j)); a += (v[j][0] * w[0] + v[j][1] * w[1]) + (v[j][2] * w[2] + v[j][3] * w[3]); }
;                 fl[q] = wave_sum(a); }
	v_mul_f32_e32 v75, v61, v79
	v_mul_f32_e32 v76, v59, v81
	ds_bpermute_b32 v82, v167, v57
	v_fmac_f32_e32 v75, v60, v78
	v_fmac_f32_e32 v76, v58, v80
	v_add_f32_e32 v74, v85, v74
	v_add_f32_e32 v75, v75, v76
	v_add_f32_e32 v74, v74, v75
	ds_bpermute_b32 v84, v169, v83
	ds_bpermute_b32 v75, v165, v74
	s_waitcnt lgkmcnt(2)
	v_add_f32_e32 v57, v57, v82
	ds_bpermute_b32 v76, v166, v57
	s_waitcnt lgkmcnt(2)
	v_add_f32_e32 v77, v83, v84
	s_waitcnt lgkmcnt(1)
	v_add_f32_e32 v74, v74, v75
	ds_bpermute_b32 v78, v168, v77
	ds_bpermute_b32 v75, v169, v74
	s_waitcnt lgkmcnt(2)
	v_add_f32_e32 v57, v57, v76
	ds_bpermute_b32 v76, v164, v57
	s_waitcnt lgkmcnt(2)
	v_add_f32_e32 v78, v77, v78
	s_waitcnt lgkmcnt(1)
	v_add_f32_e32 v80, v74, v75
	ds_bpermute_b32 v79, v167, v78
	ds_bpermute_b32 v81, v168, v80
	s_waitcnt lgkmcnt(2)
	v_add_f32_e32 v57, v57, v76
	ds_read_b128 v[74:77], v72 offset:12288
	s_waitcnt lgkmcnt(2)
	v_add_f32_e32 v82, v78, v79
	s_waitcnt lgkmcnt(1)
	v_add_f32_e32 v84, v80, v81
	ds_read_b128 v[78:81], v72 offset:12304
	s_waitcnt lgkmcnt(1)
	v_mul_f32_e32 v75, v65, v75
	v_fmac_f32_e32 v75, v64, v74
	v_mul_f32_e32 v74, v63, v77
	v_fmac_f32_e32 v74, v62, v76
	v_add_f32_e32 v74, v75, v74
	s_waitcnt lgkmcnt(0)
	v_mul_f32_e32 v79, v67, v79
	v_add_f32_e32 v85, 0, v74
	v_fmac_f32_e32 v79, v66, v78
	v_mul_f32_e32 v78, v33, v81
	ds_read_b128 v[74:77], v72 offset:14336
	v_fmac_f32_e32 v78, v32, v80
	v_add_f32_e32 v78, v79, v78
	v_add_f32_e32 v85, v85, v78
	ds_read_b128 v[78:81], v72 offset:14352
	s_waitcnt lgkmcnt(1)
	v_mul_f32_e32 v75, v31, v75
	v_fmac_f32_e32 v75, v30, v74
	v_mul_f32_e32 v74, v29, v77
	v_fmac_f32_e32 v74, v28, v76
	v_add_f32_e32 v74, v75, v74
	s_waitcnt lgkmcnt(0)
	v_mul_f32_e32 v79, v61, v79
	v_add_f32_e32 v85, v85, v74
	v_fmac_f32_e32 v79, v60, v78
	v_mul_f32_e32 v78, v59, v81
	ds_read_b128 v[74:77], v72 offset:16384
	v_fmac_f32_e32 v78, v58, v80
	v_add_f32_e32 v78, v79, v78
	v_add_f32_e32 v85, v85, v78
	ds_read_b128 v[78:81], v72 offset:16400
	s_waitcnt lgkmcnt(1)
	v_mul_f32_e32 v75, v65, v75
	v_fmac_f32_e32 v75, v64, v74
	v_mul_f32_e32 v74, v63, v77
	v_fmac_f32_e32 v74, v62, v76
	v_add_f32_e32 v74, v75, v74
	s_waitcnt lgkmcnt(0)
	v_mul_f32_e32 v79, v67, v79
	v_add_f32_e32 v87, 0, v74
	v_fmac_f32_e32 v79, v66, v78
	v_mul_f32_e32 v78, v33, v81
	ds_read_b128 v[74:77], v72 offset:18432
	v_fmac_f32_e32 v78, v32, v80
	v_add_f32_e32 v78, v79, v78
	v_add_f32_e32 v87, v87, v78
	ds_read_b128 v[78:81], v72 offset:18448
	s_waitcnt lgkmcnt(1)
	v_mul_f32_e32 v75, v31, v75
	v_fmac_f32_e32 v75, v30, v74
	v_mul_f32_e32 v74, v29, v77
	v_fmac_f32_e32 v74, v28, v76
	v_add_f32_e32 v74, v75, v74
	s_waitcnt lgkmcnt(0)
	v_mul_f32_e32 v75, v61, v79
	v_mul_f32_e32 v76, v59, v81
	v_fmac_f32_e32 v75, v60, v78
	v_fmac_f32_e32 v76, v58, v80
	v_add_f32_e32 v74, v87, v74
	v_add_f32_e32 v75, v75, v76
	v_add_f32_e32 v74, v74, v75
	ds_bpermute_b32 v86, v165, v85
	ds_bpermute_b32 v75, v165, v74
	ds_bpermute_b32 v76, v167, v84
	ds_bpermute_b32 v83, v166, v82
	s_waitcnt lgkmcnt(3)
	v_add_f32_e32 v77, v85, v86
	s_waitcnt lgkmcnt(2)
	v_add_f32_e32 v74, v74, v75
	ds_bpermute_b32 v78, v169, v77
	ds_bpermute_b32 v75, v169, v74
	s_waitcnt lgkmcnt(3)
	v_add_f32_e32 v76, v84, v76
	ds_bpermute_b32 v80, v166, v76
	s_waitcnt lgkmcnt(3)
	v_add_f32_e32 v79, v82, v83
	s_waitcnt lgkmcnt(2)
	v_add_f32_e32 v77, v77, v78
	s_waitcnt lgkmcnt(1)
	v_add_f32_e32 v74, v74, v75
	ds_bpermute_b32 v78, v168, v77
	ds_bpermute_b32 v75, v168, v74
	ds_bpermute_b32 v81, v164, v79
	s_waitcnt lgkmcnt(3)
	v_add_f32_e32 v76, v76, v80
	ds_bpermute_b32 v82, v164, v76
	s_waitcnt lgkmcnt(3)
	v_add_f32_e32 v77, v77, v78
	s_waitcnt lgkmcnt(2)
	v_add_f32_e32 v75, v74, v75
	ds_bpermute_b32 v78, v167, v77
	ds_bpermute_b32 v80, v167, v75
	s_waitcnt lgkmcnt(3)
	v_add_f32_e32 v74, v79, v81
	s_waitcnt lgkmcnt(1)
	v_add_f32_e32 v77, v77, v78
	s_waitcnt lgkmcnt(0)
	v_add_f32_e32 v79, v75, v80
	ds_bpermute_b32 v78, v166, v77
	ds_bpermute_b32 v84, v166, v79
	v_add_f32_e32 v75, v76, v82
	ds_read_b128 v[80:83], v72 offset:20480
	s_waitcnt lgkmcnt(2)
	v_add_f32_e32 v76, v77, v78
	s_waitcnt lgkmcnt(1)
	v_add_f32_e32 v78, v79, v84
	ds_read_b128 v[84:87], v72 offset:20496
	s_waitcnt lgkmcnt(1)
	v_mul_f32_e32 v81, v65, v81
	v_fmac_f32_e32 v81, v64, v80
	v_mul_f32_e32 v80, v63, v83
	v_fmac_f32_e32 v80, v62, v82
	v_add_f32_e32 v80, v81, v80
	s_waitcnt lgkmcnt(0)
	v_mul_f32_e32 v85, v67, v85
	v_add_f32_e32 v88, 0, v80
	v_fmac_f32_e32 v85, v66, v84
	v_mul_f32_e32 v84, v33, v87
	ds_read_b128 v[80:83], v72 offset:22528
	v_fmac_f32_e32 v84, v32, v86
	v_add_f32_e32 v84, v85, v84
	v_add_f32_e32 v88, v88, v84
	ds_read_b128 v[84:87], v72 offset:22544
	s_waitcnt lgkmcnt(1)
	v_mul_f32_e32 v81, v31, v81
	v_fmac_f32_e32 v81, v30, v80
	v_mul_f32_e32 v80, v29, v83
	v_fmac_f32_e32 v80, v28, v82
	v_add_f32_e32 v80, v81, v80
	s_waitcnt lgkmcnt(0)
	v_mul_f32_e32 v81, v61, v85
	v_fmac_f32_e32 v81, v60, v84
	ds_read_b128 v[82:85], v72 offset:24576
	v_mul_f32_e32 v87, v59, v87
	v_fmac_f32_e32 v87, v58, v86
	v_add_f32_e32 v80, v88, v80
	v_add_f32_e32 v81, v81, v87
	ds_read_b128 v[86:89], v72 offset:24592
	s_waitcnt lgkmcnt(1)
	v_pk_mul_f32 v[82:83], v[64:65], v[82:83]
	v_pk_mul_f32 v[84:85], v[62:63], v[84:85]
	v_add_f32_e32 v80, v80, v81
	v_pk_mov_b32 v[90:91], v[82:83], v[84:85] op_sel:[1,0]
	v_mov_b32_e32 v83, v85
	v_pk_add_f32 v[82:83], v[90:91], v[82:83]
	s_waitcnt lgkmcnt(0)
	v_pk_mul_f32 v[86:87], v[66:67], v[86:87]
	v_add_f32_e32 v82, v82, v83
	v_add_f32_e32 v94, 0, v82
	ds_read_b128 v[82:85], v72 offset:26624
	ds_read_b128 v[90:93], v72 offset:26640
	v_pk_mul_f32 v[88:89], v[32:33], v[88:89]
	ds_bpermute_b32 v81, v165, v80
	v_pk_mov_b32 v[96:97], v[86:87], v[88:89] op_sel:[1,0]
	v_mov_b32_e32 v87, v89
	v_pk_add_f32 v[86:87], v[96:97], v[86:87]
	s_waitcnt lgkmcnt(1)
; #define LAS __attribute__((address_space(3)))
; template <int LO, int HI> __global__ void __launch_bounds__(NWAVES * 64, 2) fox_fwd(Args args) {
;     ...
;             for (int q = 0; q < 8; ++q) { float a = 0.f;
; #pragma unroll
;                 for (int j = 0; j < 4; ++j) { const f32x4 w = *(const LAS f32x4*)(wf + q * 1024 + P1COL(j)); a += (v[j][0] * w[0] + v[j][1] * w[1]) + (v[j][2] * w[2] + v[j][3] * w[3]); }
;                 fl[q] = wave_sum(a); }
;             float mine = fl[0];
; #pragma unroll
;             for (int q = 1; q < 8; ++q) mine = (lane == q) ? fl[q] : mine;
;             { const float z = mine + bfv; const float ls = fminf(z, 0.f) - log1pf(__expf(-fabsf(z)));
	v_mul_f32_e32 v88, v61, v91
	v_pk_add_f32 v[86:87], v[86:87], v[86:87] op_sel:[0,1] op_sel_hi:[1,0]
	v_mul_f32_e32 v95, v60, v90
	v_mov_b32_e32 v87, v88
	v_pk_add_f32 v[88:89], v[94:95], v[86:87]
	v_mul_f32_e32 v86, v31, v83
	v_pk_fma_f32 v[82:83], v[30:31], v[82:83], v[86:87] op_sel_hi:[1,1,0]
	v_mul_f32_e32 v86, v29, v85
	v_mul_f32_e32 v90, v58, v92
	v_mul_f32_e32 v91, v59, v93
	v_pk_fma_f32 v[84:85], v[28:29], v[84:85], v[86:87] op_sel_hi:[1,1,0]
	v_mov_b32_e32 v83, v90
	v_mov_b32_e32 v85, v91
	v_pk_add_f32 v[82:83], v[82:83], v[84:85]
	ds_read_b128 v[84:87], v72 offset:28672
	v_pk_add_f32 v[82:83], v[88:89], v[82:83]
	ds_read_b128 v[88:91], v72 offset:28688
	v_add_f32_e32 v82, v82, v83
	ds_bpermute_b32 v83, v165, v82
	s_waitcnt lgkmcnt(2)
	v_pk_mul_f32 v[64:65], v[64:65], v[84:85]
	v_pk_mul_f32 v[62:63], v[62:63], v[86:87]
	s_waitcnt lgkmcnt(1)
	v_pk_mul_f32 v[66:67], v[66:67], v[88:89]
	v_pk_mov_b32 v[84:85], v[64:65], v[62:63] op_sel:[1,0]
	v_mov_b32_e32 v65, v63
	v_pk_add_f32 v[62:63], v[84:85], v[64:65]
	v_pk_mul_f32 v[32:33], v[32:33], v[90:91]
	v_add_f32_e32 v62, v62, v63
	v_add_f32_e32 v92, 0, v62
	ds_read_b128 v[62:65], v72 offset:30720
	ds_read_b128 v[84:87], v72 offset:30736
	v_pk_mov_b32 v[88:89], v[66:67], v[32:33] op_sel:[1,0]
	v_mov_b32_e32 v67, v33
	v_pk_add_f32 v[32:33], v[88:89], v[66:67]
	ds_bpermute_b32 v77, v164, v76
	s_waitcnt lgkmcnt(1)
	v_mul_f32_e32 v93, v60, v84
	v_mul_f32_e32 v60, v61, v85
	v_mul_f32_e32 v61, v58, v86
	v_mul_f32_e32 v59, v59, v87
	v_mul_f32_e32 v58, v31, v63
	v_pk_fma_f32 v[30:31], v[30:31], v[62:63], v[58:59] op_sel_hi:[1,1,0]
	v_mul_f32_e32 v58, v29, v65
	v_pk_add_f32 v[32:33], v[32:33], v[32:33] op_sel:[0,1] op_sel_hi:[1,0]
	v_pk_fma_f32 v[28:29], v[28:29], v[64:65], v[58:59] op_sel_hi:[1,1,0]
	v_mov_b32_e32 v33, v60
	v_mov_b32_e32 v31, v61
	v_mov_b32_e32 v29, v59
	v_pk_add_f32 v[32:33], v[92:93], v[32:33]
	v_pk_add_f32 v[28:29], v[30:31], v[28:29]
	v_add_f32_e32 v30, v80, v81
	v_pk_add_f32 v[28:29], v[32:33], v[28:29]
	ds_bpermute_b32 v31, v169, v30
	v_add_f32_e32 v28, v28, v29
	ds_bpermute_b32 v29, v165, v28
	v_add_f32_e32 v32, v82, v83
	ds_bpermute_b32 v33, v169, v32
	s_waitcnt lgkmcnt(2)
	v_add_f32_e32 v30, v30, v31
	ds_bpermute_b32 v31, v168, v30
	s_waitcnt lgkmcnt(2)
	v_add_f32_e32 v28, v28, v29
	ds_bpermute_b32 v29, v169, v28
	s_waitcnt lgkmcnt(2)
	v_add_f32_e32 v32, v32, v33
	ds_bpermute_b32 v33, v168, v32
	s_waitcnt lgkmcnt(2)
	v_add_f32_e32 v30, v30, v31
	ds_bpermute_b32 v31, v167, v30
	s_waitcnt lgkmcnt(2)
	v_add_f32_e32 v28, v28, v29
	ds_bpermute_b32 v29, v168, v28
	s_waitcnt lgkmcnt(2)
	v_add_f32_e32 v32, v32, v33
	ds_bpermute_b32 v33, v167, v32
	s_waitcnt lgkmcnt(2)
	v_add_f32_e32 v30, v30, v31
	ds_bpermute_b32 v31, v166, v30
	s_waitcnt lgkmcnt(2)
	v_add_f32_e32 v28, v28, v29
	ds_bpermute_b32 v29, v167, v28
	s_waitcnt lgkmcnt(2)
	v_add_f32_e32 v32, v32, v33
	ds_bpermute_b32 v33, v166, v32
	ds_bpermute_b32 v79, v164, v78
	s_waitcnt lgkmcnt(3)
	v_add_f32_e32 v30, v30, v31
	s_waitcnt lgkmcnt(2)
	v_add_f32_e32 v28, v28, v29
	ds_bpermute_b32 v29, v166, v28
	ds_bpermute_b32 v31, v164, v30
	s_waitcnt lgkmcnt(3)
	v_add_f32_e32 v32, v32, v33
	ds_bpermute_b32 v33, v164, v32
	v_add_f32_e32 v58, v76, v77
	s_waitcnt lgkmcnt(2)
	v_add_f32_e32 v28, v28, v29
	ds_bpermute_b32 v29, v164, v28
	v_add_f32_e32 v59, v78, v79
	s_waitcnt lgkmcnt(2)
	v_add_f32_e32 v30, v30, v31
	s_waitcnt lgkmcnt(1)
	v_add_f32_e32 v31, v32, v33
	global_store_dwordx4 v[24:25], v[18:21], off offset:1024
	s_waitcnt lgkmcnt(0)
	v_add_f32_e32 v28, v28, v29
	v_cndmask_b32_e64 v29, v57, v74, s[4:5]
	v_cndmask_b32_e64 v29, v29, v75, s[6:7]
	v_cndmask_b32_e64 v29, v29, v58, s[8:9]
	v_cndmask_b32_e64 v29, v29, v59, s[10:11]
	v_cndmask_b32_e64 v29, v29, v30, s[12:13]
	v_cndmask_b32_e64 v29, v29, v31, s[14:15]
	v_cndmask_b32_e64 v28, v29, v28, s[16:17]
	v_add_f32_e32 v29, v71, v28
	v_mul_f32_e64 v28, |v29|, s29
	v_exp_f32_e32 v78, v28
	v_ldexp_f32 v28, v23, v27
	v_min_f32_e32 v23, 0, v29
	v_add_f32_e32 v20, 1.0, v78
	v_add_f32_e32 v18, -1.0, v20
	v_sub_f32_e32 v19, v18, v20
	v_add_f32_e32 v19, 1.0, v19
	v_sub_f32_e32 v18, v78, v18
	v_add_f32_e32 v21, v18, v19
	v_frexp_mant_f32_e32 v24, v20
	v_cvt_f64_f32_e32 v[18:19], v20
	v_frexp_exp_i32_f64_e32 v18, v[18:19]
	v_cmp_gt_f32_e32 vcc, s37, v24
	s_nop 1
	v_subbrev_co_u32_e32 v57, vcc, 0, v18, vcc
	v_sub_u32_e32 v18, 0, v57
	v_ldexp_f32 v27, v20, v18
	v_ldexp_f32 v29, v21, v18
	v_pk_add_f32 v[18:19], v[26:27], 1.0 op_sel_hi:[1,0]
	v_pk_add_f32 v[32:33], v[26:27], -1.0 op_sel_hi:[1,0]
	v_pk_add_f32 v[20:21], v[18:19], -1.0 op_sel_hi:[1,0]
	v_pk_add_f32 v[58:59], v[32:33], 1.0 op_sel_hi:[1,0]
	v_pk_add_f32 v[20:21], v[26:27], v[20:21] neg_lo:[0,1] neg_hi:[0,1]
	v_pk_add_f32 v[26:27], v[26:27], v[58:59] neg_lo:[0,1] neg_hi:[0,1]
	v_pk_add_f32 v[20:21], v[28:29], v[20:21]
	v_pk_add_f32 v[26:27], v[28:29], v[26:27]
	v_pk_add_f32 v[24:25], v[18:19], v[20:21]
	v_pk_add_f32 v[28:29], v[32:33], v[26:27]
	v_rcp_f32_e32 v30, v24
	v_rcp_f32_e32 v31, v25
	v_pk_add_f32 v[18:19], v[24:25], v[18:19] neg_lo:[0,1] neg_hi:[0,1]
	v_pk_add_f32 v[32:33], v[28:29], v[32:33] neg_lo:[0,1] neg_hi:[0,1]
	v_pk_add_f32 v[18:19], v[20:21], v[18:19] neg_lo:[0,1] neg_hi:[0,1]
	v_pk_mul_f32 v[20:21], v[28:29], v[30:31]
	v_pk_add_f32 v[26:27], v[26:27], v[32:33] neg_lo:[0,1] neg_hi:[0,1]
	v_pk_mul_f32 v[32:33], v[24:25], v[20:21]
	v_cmp_neq_f32_e32 vcc, s46, v55
	v_pk_fma_f32 v[58:59], v[20:21], v[24:25], v[32:33] neg_lo:[0,0,1] neg_hi:[0,0,1]
	s_nop 0
	v_pk_fma_f32 v[58:59], v[20:21], v[18:19], v[58:59]
	s_nop 0
	v_pk_add_f32 v[60:61], v[32:33], v[58:59]
	s_nop 0
	v_pk_add_f32 v[62:63], v[28:29], v[60:61] neg_lo:[0,1] neg_hi:[0,1]
; template <int LO, int HI> __global__ void __launch_bounds__(NWAVES * 64, 2) fox_fwd(Args args) {
;     ...
;             { const float z = mine + bfv; const float ls = fminf(z, 0.f) - log1pf(__expf(-fabsf(z)));
; #pragma unroll
;               for (int k = 0; k < 4; ++k)
; #pragma unroll
;                   for (int e = 0; e < 4; ++e) lsq[k][e] = (r == 4 * k + e) ? ls : lsq[k][e]; }
	v_pk_add_f32 v[32:33], v[60:61], v[32:33] neg_lo:[0,1] neg_hi:[0,1]
	v_pk_add_f32 v[28:29], v[28:29], v[62:63] neg_lo:[0,1] neg_hi:[0,1]
	s_nop 0
	v_pk_add_f32 v[28:29], v[28:29], v[60:61] neg_lo:[0,1] neg_hi:[0,1]
	s_nop 0
	v_pk_add_f32 v[26:27], v[26:27], v[28:29]
	v_pk_add_f32 v[28:29], v[32:33], v[58:59] neg_lo:[0,1] neg_hi:[0,1]
	s_nop 0
	v_pk_add_f32 v[26:27], v[28:29], v[26:27]
	s_nop 0
	v_pk_add_f32 v[28:29], v[62:63], v[26:27]
	s_nop 0
	v_pk_mul_f32 v[32:33], v[30:31], v[28:29]
	s_nop 0
	v_pk_mul_f32 v[58:59], v[24:25], v[32:33]
	s_nop 0
	v_pk_fma_f32 v[24:25], v[32:33], v[24:25], v[58:59] neg_lo:[0,0,1] neg_hi:[0,0,1]
	s_nop 0
	v_pk_fma_f32 v[18:19], v[32:33], v[18:19], v[24:25]
	v_pk_add_f32 v[24:25], v[62:63], v[28:29] neg_lo:[0,1] neg_hi:[0,1]
	s_nop 0
	v_pk_add_f32 v[24:25], v[26:27], v[24:25]
	v_pk_add_f32 v[26:27], v[58:59], v[18:19]
	s_nop 0
	v_pk_add_f32 v[60:61], v[28:29], v[26:27] neg_lo:[0,1] neg_hi:[0,1]
	v_pk_add_f32 v[58:59], v[26:27], v[58:59] neg_lo:[0,1] neg_hi:[0,1]
	v_pk_add_f32 v[28:29], v[28:29], v[60:61] neg_lo:[0,1] neg_hi:[0,1]
	v_pk_add_f32 v[18:19], v[58:59], v[18:19] neg_lo:[0,1] neg_hi:[0,1]
	v_pk_add_f32 v[26:27], v[28:29], v[26:27] neg_lo:[0,1] neg_hi:[0,1]
	s_nop 0
	v_pk_add_f32 v[24:25], v[24:25], v[26:27]
	s_nop 0
	v_pk_add_f32 v[18:19], v[18:19], v[24:25]
	v_pk_add_f32 v[24:25], v[20:21], v[32:33]
	v_pk_add_f32 v[18:19], v[60:61], v[18:19]
	v_pk_add_f32 v[20:21], v[24:25], v[20:21] neg_lo:[0,1] neg_hi:[0,1]
	v_pk_mul_f32 v[18:19], v[30:31], v[18:19]
	v_pk_add_f32 v[20:21], v[32:33], v[20:21] neg_lo:[0,1] neg_hi:[0,1]
	v_cvt_f32_i32_e32 v32, v56
	v_pk_add_f32 v[18:19], v[20:21], v[18:19]
	v_cvt_f32_i32_e32 v33, v57
	v_pk_add_f32 v[26:27], v[24:25], v[18:19]
	s_nop 0
	v_pk_add_f32 v[20:21], v[26:27], v[24:25] neg_lo:[0,1] neg_hi:[0,1]
	v_pk_mul_f32 v[28:29], v[26:27], v[26:27]
	v_pk_add_f32 v[18:19], v[18:19], v[20:21] neg_lo:[0,1] neg_hi:[0,1]
	v_mov_b32_e32 v20, 0x3ecc95a3
	v_pk_fma_f32 v[30:31], v[28:29], s[20:21], v[20:21] op_sel_hi:[1,0,0]
	s_mov_b32 s20, 0x3f2aaada
	v_ldexp_f32 v24, v26, 1
	v_pk_fma_f32 v[30:31], v[28:29], v[30:31], s[20:21] op_sel_hi:[1,1,0]
	v_ldexp_f32 v25, v27, 1
	v_pk_mul_f32 v[26:27], v[26:27], v[28:29]
	v_pk_mul_f32 v[28:29], v[32:33], s[36:37] op_sel_hi:[1,0]
	v_pk_mul_f32 v[26:27], v[26:27], v[30:31]
	v_pk_fma_f32 v[58:59], v[32:33], s[36:37], v[28:29] op_sel_hi:[1,0,1] neg_lo:[0,0,1] neg_hi:[0,0,1]
	v_pk_add_f32 v[30:31], v[24:25], v[26:27]
	s_mov_b32 s20, 0xb102e308
	v_pk_add_f32 v[24:25], v[30:31], v[24:25] neg_lo:[0,1] neg_hi:[0,1]
	v_ldexp_f32 v57, v19, 1
	v_pk_fma_f32 v[32:33], v[32:33], s[20:21], v[58:59] op_sel_hi:[1,0,1]
	v_pk_add_f32 v[24:25], v[26:27], v[24:25] neg_lo:[0,1] neg_hi:[0,1]
	v_ldexp_f32 v18, v18, 1
	v_mov_b32_e32 v26, v28
	v_mov_b32_e32 v27, v25
	v_mov_b32_e32 v56, v32
	v_mov_b32_e32 v19, v57
	v_pk_add_f32 v[26:27], v[26:27], v[56:57]
	v_pk_add_f32 v[56:57], v[18:19], v[24:25]
	v_mov_b32_e32 v25, v31
	v_mov_b32_e32 v19, v57
	v_pk_add_f32 v[58:59], v[28:29], v[32:33]
	v_pk_add_f32 v[18:19], v[18:19], v[24:25]
	v_pk_add_f32 v[24:25], v[30:31], v[56:57]
	v_mov_b32_e32 v74, v30
	v_pk_add_f32 v[60:61], v[58:59], v[24:25]
	v_mov_b32_e32 v66, v24
	v_mov_b32_e32 v67, v61
	v_mov_b32_e32 v75, v59
	v_pk_add_f32 v[66:67], v[66:67], v[74:75] neg_lo:[0,1] neg_hi:[0,1]
	v_mov_b32_e32 v62, v60
	v_mov_b32_e32 v63, v59
	v_mov_b32_e32 v64, v58
	v_mov_b32_e32 v65, v29
	v_mov_b32_e32 v74, v58
	v_mov_b32_e32 v75, v61
	v_mov_b32_e32 v29, v67
	v_pk_add_f32 v[62:63], v[62:63], v[64:65] neg_lo:[0,1] neg_hi:[0,1]
	v_mov_b32_e32 v64, v24
	v_mov_b32_e32 v65, v33
	v_pk_add_f32 v[28:29], v[74:75], v[28:29] neg_lo:[0,1] neg_hi:[0,1]
	v_pk_add_f32 v[64:65], v[64:65], v[62:63] neg_lo:[0,1] neg_hi:[0,1]
	v_mov_b32_e32 v74, v28
	v_mov_b32_e32 v75, v63
	v_mov_b32_e32 v76, v60
	v_mov_b32_e32 v77, v25
	v_mov_b32_e32 v63, v31
	v_pk_add_f32 v[74:75], v[32:33], v[74:75] neg_lo:[0,1] neg_hi:[0,1]
	v_pk_add_f32 v[62:63], v[76:77], v[62:63] neg_lo:[0,1] neg_hi:[0,1]
	v_mov_b32_e32 v33, v59
	v_pk_add_f32 v[26:27], v[26:27], v[62:63] neg_lo:[0,1] neg_hi:[0,1]
	v_pk_add_f32 v[28:29], v[32:33], v[28:29] neg_lo:[0,1] neg_hi:[0,1]
	v_pk_add_f32 v[18:19], v[18:19], v[66:67] neg_lo:[0,1] neg_hi:[0,1]
	v_pk_add_f32 v[24:25], v[24:25], v[30:31] neg_lo:[0,1] neg_hi:[0,1]
	v_pk_add_f32 v[30:31], v[18:19], v[28:29]
	v_mov_b32_e32 v29, v65
	v_mov_b32_e32 v19, v27
	v_pk_add_f32 v[32:33], v[64:65], v[26:27]
	v_pk_add_f32 v[18:19], v[28:29], v[18:19]
	v_mov_b32_e32 v26, v30
	v_pk_add_f32 v[18:19], v[18:19], v[74:75] neg_lo:[0,1] neg_hi:[0,1]
	v_mov_b32_e32 v27, v33
	v_pk_add_f32 v[24:25], v[56:57], v[24:25] neg_lo:[0,1] neg_hi:[0,1]
	v_pk_add_f32 v[26:27], v[26:27], v[18:19] neg_lo:[0,1] neg_hi:[0,1]
	v_pk_add_f32 v[18:19], v[24:25], v[18:19] neg_lo:[0,1] neg_hi:[0,1]
	v_pk_add_f32 v[26:27], v[28:29], v[26:27] neg_lo:[0,1] neg_hi:[0,1]
	v_pk_add_f32 v[24:25], v[32:33], v[30:31]
	v_pk_add_f32 v[18:19], v[18:19], v[26:27]
	v_pk_add_f32 v[26:27], v[60:61], v[24:25]
	v_mov_b32_e32 v64, 0x7f800000
; #define GAS __attribute__((address_space(1)))
; template <int LO, int HI> __global__ void __launch_bounds__(NWAVES * 64, 2) fox_fwd(Args args) {
;     ...
;         for (int r = 0; r < 16; ++r) { const int m = m0 + r;
;             const GAS float* xr = (const GAS float*)(x + (size_t)m * D);
;             f32x4 v[4]; float s2 = 0.f;
; #pragma unroll
;             for (int j = 0; j < 4; ++j) { v[j] = *(const GAS f32x4*)(xr + P1COL(j)); s2 += (v[j][0] * v[j][0] + v[j][1] * v[j][1]) + (v[j][2] * v[j][2] + v[j][3] * v[j][3]); }
;     ...
;             { const float z = mine + bfv; const float ls = fminf(z, 0.f) - log1pf(__expf(-fabsf(z)));
; #pragma unroll
;               for (int k = 0; k < 4; ++k)
; #pragma unroll
;                   for (int e = 0; e < 4; ++e) lsq[k][e] = (r == 4 * k + e) ? ls : lsq[k][e]; }
	v_pk_add_f32 v[28:29], v[26:27], v[60:61] neg_lo:[0,1] neg_hi:[0,1]
	v_mov_b32_e32 v65, 0x7fc00000
	v_pk_add_f32 v[24:25], v[24:25], v[28:29] neg_lo:[0,1] neg_hi:[0,1]
	v_mov_b32_e32 v66, 0xff800000
	v_pk_add_f32 v[18:19], v[18:19], v[24:25]
	s_add_u32 s20, s26, s34
	v_pk_add_f32 v[18:19], v[26:27], v[18:19]
	s_addc_u32 s21, s27, s35
	v_cndmask_b32_e32 v18, v64, v18, vcc
	v_cmp_neq_f32_e32 vcc, s46, v78
	s_mov_b64 s[34:35], 0x2000
	v_mov_b32_e32 v58, 0x3f317218
	v_cndmask_b32_e32 v19, v64, v19, vcc
	v_cmp_ngt_f32_e32 vcc, -1.0, v78
	v_mov_b32_e32 v21, v37
	v_mov_b32_e32 v30, v37
	v_cndmask_b32_e32 v19, v65, v19, vcc
	v_cmp_ngt_f32_e32 vcc, -1.0, v55
	v_mov_b32_e32 v31, v37
	v_mov_b32_e32 v32, v37
	v_cndmask_b32_e32 v18, v65, v18, vcc
	v_cmp_neq_f32_e32 vcc, -1.0, v55
	v_mov_b32_e32 v33, v37
	v_mov_b32_e32 v26, v37
	v_cndmask_b32_e32 v18, v66, v18, vcc
	v_cmp_neq_f32_e32 vcc, -1.0, v78
	v_mov_b32_e32 v27, v37
	v_mov_b32_e32 v28, v37
	v_cndmask_b32_e32 v19, v66, v19, vcc
	v_cmp_lt_f32_e64 vcc, |v78|, s47
	v_mov_b32_e32 v29, v37
	v_mov_b32_e32 v24, v37
	v_cndmask_b32_e32 v19, v19, v78, vcc
	v_cmp_lt_f32_e64 vcc, |v55|, s47
	v_mov_b32_e32 v25, v37
	s_nop 0
	v_cndmask_b32_e32 v18, v18, v55, vcc
	v_pk_add_f32 v[18:19], v[22:23], v[18:19] neg_lo:[0,1] neg_hi:[0,1]
	v_mov_b32_e32 v55, v37
	v_lshl_add_u64 v[22:23], s[20:21], 0, v[36:37]
	s_mov_b64 s[20:21], 0x2001400
	v_lshl_add_u64 v[54:55], s[30:31], 0, v[54:55]
	v_lshl_add_u64 v[56:57], v[22:23], 0, s[20:21]
	s_mov_b64 s[30:31], 0
	v_mov_b32_e32 v22, v37
	v_mov_b32_e32 v23, v37
	ds_read_b128 v[100:103], v72
	ds_read_b128 v[104:107], v72 offset:16
	ds_read_b128 v[108:111], v72 offset:2048
	ds_read_b128 v[112:115], v72 offset:2064
	ds_read_b128 v[116:119], v72 offset:4096
	ds_read_b128 v[120:123], v72 offset:4112
	ds_read_b128 v[124:127], v72 offset:6144
	ds_read_b128 v[128:131], v72 offset:6160
	ds_read_b128 v[132:135], v72 offset:8192
	ds_read_b128 v[136:139], v72 offset:8208
	ds_read_b128 v[140:143], v72 offset:10240
	ds_read_b128 v[144:147], v72 offset:10256
	s_waitcnt lgkmcnt(0)
	ds_read_b128 v[148:151], v72 offset:12288
	ds_read_b128 v[152:155], v72 offset:12304
	ds_read_b128 v[156:159], v72 offset:14336
	ds_read_b128 v[170:173], v72 offset:14352
	ds_read_b128 v[174:177], v72 offset:16384
	ds_read_b128 v[178:181], v72 offset:16400
	ds_read_b128 v[182:185], v72 offset:18432
	ds_read_b128 v[186:189], v72 offset:18448
	ds_read_b128 v[190:193], v72 offset:20480
	ds_read_b128 v[194:197], v72 offset:20496
	ds_read_b128 v[198:201], v72 offset:22528
	ds_read_b128 v[202:205], v72 offset:22544
	s_waitcnt lgkmcnt(0)
	ds_read_b128 v[206:209], v72 offset:24576
	ds_read_b128 v[210:213], v72 offset:24592
	ds_read_b128 v[226:229], v72 offset:26624
	ds_read_b128 v[230:233], v72 offset:26640
	ds_read_b128 v[234:237], v72 offset:28672
	ds_read_b128 v[238:241], v72 offset:28688
	ds_read_b128 v[242:245], v72 offset:30720
	ds_read_b128 v[246:249], v72 offset:30736
	s_waitcnt lgkmcnt(0)
	s_mov_b32 s52, m0
	s_mov_b64 s[56:57], 0x2000
	s_mov_b64 s[58:59], 0x400
	s_mov_b64 s[60:61], 0x800
	v_lshrrev_b32_e32 v224, 6, v0
	v_mbcnt_lo_u32_b32 v225, -1, 0
	v_mbcnt_hi_u32_b32 v225, -1, v225
	v_readfirstlane_b32 s50, v224
	v_lshlrev_b32_e32 v224, 5, v225
	v_lshlrev_b32_e32 v252, 4, v225
	v_sub_u32_e32 v252, 0, v252
	v_ashrrev_i32_e32 v253, 31, v252
	s_lshl_b32 s50, s50, 12
	s_add_i32 s50, s50, 0x11000
	s_mov_b32 s53, 0
	v_mov_b32_e32 v160, s53
	v_mov_b32_e32 v161, 0
	v_lshl_add_u64 v[160:161], v[54:55], 0, v[160:161]
	v_lshl_add_u64 v[160:161], v[160:161], 0, s[56:57]
	v_lshl_add_u64 v[250:251], v[160:161], 0, v[252:253]
	v_lshl_add_u64 v[254:255], v[250:251], 0, s[60:61]
	s_mov_b32 m0, s50
	s_nop 0
	global_load_lds_dwordx4 v[250:251], off
	v_lshl_add_u64 v[250:251], v[250:251], 0, s[58:59]
	s_add_i32 m0, s50, 0x400
	s_nop 0
	global_load_lds_dwordx4 v[250:251], off
	s_add_i32 m0, s50, 0x800
	s_nop 0
	global_load_lds_dwordx4 v[254:255], off
	v_lshl_add_u64 v[254:255], v[254:255], 0, s[58:59]
	s_add_i32 m0, s50, 0xc00
	s_nop 0
	global_load_lds_dwordx4 v[254:255], off
.LBB0_131:
	s_waitcnt vmcnt(0)
	s_barrier
	v_add_u32_e32 v225, s50, v224
	ds_read_b128 v[60:63], v225
	ds_read_b128 v[74:77], v225 offset:16
	ds_read_b128 v[78:81], v225 offset:2064
	ds_read_b128 v[82:85], v225 offset:2048
	s_waitcnt lgkmcnt(0)
	s_cmp_eq_u32 s30, 0xd000
	s_cbranch_scc1 .Lp1dma_skip
	s_add_i32 s53, s30, 0x1000
	v_mov_b32_e32 v160, s53
	v_mov_b32_e32 v161, 0
	v_lshl_add_u64 v[160:161], v[54:55], 0, v[160:161]
	v_lshl_add_u64 v[160:161], v[160:161], 0, s[56:57]
	v_lshl_add_u64 v[250:251], v[160:161], 0, v[252:253]
	v_lshl_add_u64 v[254:255], v[250:251], 0, s[60:61]
	s_mov_b32 m0, s50
	s_nop 0
	global_load_lds_dwordx4 v[250:251], off
	v_lshl_add_u64 v[250:251], v[250:251], 0, s[58:59]
	s_add_i32 m0, s50, 0x400
	s_nop 0
	global_load_lds_dwordx4 v[250:251], off
	s_add_i32 m0, s50, 0x800
	s_nop 0
	global_load_lds_dwordx4 v[254:255], off
	v_lshl_add_u64 v[254:255], v[254:255], 0, s[58:59]
	s_add_i32 m0, s50, 0xc00
	s_nop 0
	global_load_lds_dwordx4 v[254:255], off
